# v62 + hgC loop: next-item oi/og copies moved from the norm section (behind vmcnt(0)) to the loop head behind counted waits; queue draw issued before the prefetch and collected at the end of the norm s
# speedup vs baseline: 1.0077x; 1.0045x over previous
; __device__ __forceinline__ void hgC_loop(Frame& F, unsigned* ctr) {
;     ...
;     if (tid == 0) { slot[0] = (int)__hip_atomic_fetch_add(ctr, 1u, __ATOMIC_RELAXED, __HIP_MEMORY_SCOPE_AGENT); slot[1] = (int)__hip_atomic_fetch_add(ctr, 1u, __ATOMIC_RELAXED, __HIP_MEMORY_SCOPE_AGENT); }
;     __syncthreads();
;     int item = slot[0], nxt = slot[1], par = 0;
;     if (item >= 1024) return;
;     v4u sc[4], qh[2], oi[2]; v2u og[4];
;     ...
;     HGC_FETCH(item);
.LBB0_690:
	s_or_b64 exec, exec, s[0:1]
	v_mov_b32_e32 v55, 0
	s_waitcnt lgkmcnt(0)
	s_barrier
	ds_read_b32 v2, v55 offset:53248
	ds_read_b32 v3, v55 offset:53252
	s_movk_i32 s0, 0x3ff
	s_mov_b32 s11, 0
	s_waitcnt lgkmcnt(1)
	v_cmp_lt_i32_e32 vcc, s0, v2
	v_readfirstlane_b32 s18, v2
	s_waitcnt lgkmcnt(0)
	v_readfirstlane_b32 s17, v3
	s_cbranch_vccnz .LBB0_701
	s_lshl_b32 s0, s96, 3
	v_and_b32_e32 v12, 31, v0
	v_readlane_b32 s20, v238, 25
	s_and_b32 s0, s0, 0x1fffffe0
	s_ashr_i32 s19, s18, 31
	s_bfe_u32 s3, s20, 0x20006
	v_or_b32_e32 v90, s0, v12
	s_lshl_b64 s[0:1], s[18:19], 15
	s_add_u32 s0, s46, s0
	v_lshlrev_b32_e32 v2, 4, v0
	v_or_b32_e32 v6, 0x200, v0
	s_addc_u32 s1, s47, s1
	v_and_b32_e32 v54, 0xf0, v2
	v_lshrrev_b32_e32 v14, 4, v6
	v_lshl_add_u64 v[2:3], s[0:1], 0, v[54:55]
	v_lshlrev_b32_e32 v56, 8, v139
	v_mov_b32_e32 v57, v55
	v_lshlrev_b32_e32 v58, 8, v14
	v_mov_b32_e32 v59, v55
	s_lshl_b64 s[14:15], s[18:19], 14
	v_lshl_add_u64 v[4:5], v[2:3], 0, v[56:57]
	v_lshl_add_u64 v[6:7], v[2:3], 0, v[58:59]
	s_add_u32 s12, s48, 0x1000000
	global_load_dwordx4 v[18:21], v[4:5], off
	global_load_dwordx4 v[22:25], v[6:7], off
	v_or_b32_e32 v6, 0x600, v0
	s_addc_u32 s13, s49, 0
	s_lshl_b32 s10, s18, 4
	s_lshl_b32 s16, s18, 6
	v_lshrrev_b32_e32 v15, 4, v6
	v_or_b32_e32 v60, 0x4000, v56
	v_mov_b32_e32 v61, v55
	v_lshlrev_b32_e32 v62, 8, v15
	v_mov_b32_e32 v63, v55
	s_add_u32 s0, s48, s14
	v_lshl_add_u64 v[4:5], v[2:3], 0, v[60:61]
	v_lshl_add_u64 v[2:3], v[2:3], 0, v[62:63]
	s_addc_u32 s1, s49, s15
	s_and_b32 s10, s10, 0xfffff800
	global_load_dwordx4 v[26:29], v[4:5], off
	global_load_dwordx4 v[30:33], v[2:3], off
	v_lshl_add_u64 v[2:3], s[0:1], 0, v[54:55]
	s_add_u32 s0, s12, s14
	v_lshl_add_u64 v[4:5], v[2:3], 0, v[56:57]
	v_lshl_add_u64 v[2:3], v[2:3], 0, v[58:59]
	s_addc_u32 s1, s13, s15
	s_and_b32 s15, s20, 0xffffffc0
	global_load_dwordx4 v[34:37], v[4:5], off
	global_load_dwordx4 v[38:41], v[2:3], off
	v_or_b32_e32 v2, s15, v154
	v_mov_b32_e32 v3, v55
	s_and_b32 s14, s16, 0x7c0
	v_lshlrev_b64 v[2:3], 5, v[2:3]
	v_lshl_add_u64 v[4:5], s[0:1], 0, v[2:3]
	s_or_b32 s0, s10, s14
	global_load_dwordx4 v[42:45], v[4:5], off offset:16
	global_load_dwordx4 v[46:49], v[4:5], off
	v_add_u32_e32 v4, s0, v90
	v_ashrrev_i32_e32 v5, 31, v4
	v_lshlrev_b64 v[4:5], 12, v[4:5]
	s_lshl_b32 s0, s18, 3
	v_lshl_add_u64 v[4:5], s[56:57], 0, v[4:5]
	s_and_b32 s10, s0, 0x300
	v_lshrrev_b32_e32 v13, 5, v154
	v_lshl_add_u64 v[4:5], v[4:5], 0, s[10:11]
	s_lshl_b32 s10, s3, 6
	v_lshl_add_u64 v[4:5], v[4:5], 0, s[10:11]
	v_lshlrev_b32_e32 v10, 3, v13
	v_mov_b32_e32 v11, v55
	v_lshl_add_u64 v[4:5], v[4:5], 0, v[10:11]
	global_load_dwordx2 v[82:83], v[4:5], off offset:3072
	global_load_dwordx2 v[84:85], v[4:5], off offset:3088
	global_load_dwordx2 v[86:87], v[4:5], off offset:3104
	global_load_dwordx2 v[88:89], v[4:5], off offset:3120
	s_lshl_b32 s10, s3, 5
	s_lshl_b32 s0, s3, 2
	v_or_b32_e32 v10, s10, v12
	s_add_i32 s3, s0, 0
	s_movk_i32 s0, 0x110
	v_mul_u32_u24_e32 v10, 0x110, v10
	v_lshlrev_b32_e32 v11, 4, v13
	v_lshlrev_b32_e32 v4, 2, v13
	v_add3_u32 v91, 0, v10, v11
	v_mul_lo_u32 v10, v90, s0
	v_add3_u32 v92, 0, v10, v11
	v_or_b32_e32 v10, s10, v4
	v_readlane_b32 s68, v238, 29
	v_add_u32_e32 v5, 0, v54
	v_mul_u32_u24_e32 v11, 0x110, v139
	v_mul_u32_u24_e32 v12, 0x110, v14
	v_mul_u32_u24_e32 v13, 0x110, v15
	v_lshl_add_u64 v[64:65], s[46:47], 0, v[54:55]
	v_lshl_add_u64 v[66:67], s[48:49], 0, v[54:55]
	v_lshl_add_u64 v[68:69], s[12:13], 0, v[2:3]
	v_lshlrev_b32_e32 v54, 2, v10
	v_readlane_b32 s70, v238, 31
	v_readlane_b32 s71, v238, 32
	v_mbcnt_lo_u32_b32 v2, -1, 0
	v_cmp_gt_u32_e64 s[0:1], 32, v154
	v_lshlrev_b32_e32 v93, 4, v90
	v_lshl_add_u64 v[72:73], s[70:71], 0, v[54:55]
	global_load_dwordx4 v[198:201], v[72:73], off
	global_load_dwordx4 v[202:205], v[72:73], off offset:32
	global_load_dwordx4 v[206:209], v[72:73], off offset:64
	global_load_dwordx4 v[210:213], v[72:73], off offset:96
	v_add_u32_e32 v94, v5, v11
	v_add_u32_e32 v95, v5, v12
	v_add_u32_e32 v96, v5, v13
	s_lshl_b32 s12, s10, 1
	v_lshlrev_b32_e32 v74, 1, v4
	v_mbcnt_hi_u32_b32 v97, -1, v2
	v_mov_b32_e32 v98, 0x358637bd
	v_lshlrev_b32_e32 v54, 1, v10
	s_mov_b64 s[14:15], 0xc500400
	s_mov_b32 s19, 0xc500000
	v_mov_b32_e32 v99, v55
	v_readlane_b32 s69, v238, 30
	v_readlane_b32 s72, v238, 33
	v_readlane_b32 s73, v238, 34
	v_readlane_b32 s74, v238, 35
	v_readlane_b32 s75, v238, 36
	v_readlane_b32 s76, v238, 37
	v_readlane_b32 s77, v238, 38
	v_readlane_b32 s78, v238, 39
	v_readlane_b32 s79, v238, 40
	v_readlane_b32 s80, v238, 41
	v_readlane_b32 s81, v238, 42
	v_readlane_b32 s82, v238, 43
	v_readlane_b32 s83, v238, 44
	s_waitcnt vmcnt(0)
	s_branch .LBB0_693
; #define GAS __attribute__((address_space(1)))
; #define LAS __attribute__((address_space(3)))
; __device__ __forceinline__ unsigned pk2(float lo, float hi) { f32x2_t v = {lo, hi}; bf16x2_t h = __builtin_convertvector(v, bf16x2_t); return __builtin_bit_cast(unsigned, h); }
; __device__ __forceinline__ float siluf_(float x) { return x * __builtin_amdgcn_rcpf(1.0f + __builtin_amdgcn_exp2f(-1.4426950408889634f * x)); }
; __device__ __forceinline__ void hgC_loop(Frame& F, unsigned* ctr) {
;     ...
;         __syncthreads();
;         { const f32x4 s4 = *(const LAS f32x4*)(SS + t * 4); const float rstd = __builtin_amdgcn_rsqf(((s4.x + s4.y) + (s4.z + s4.w)) * (1.0f / HD) + EPS);
; #pragma unroll
;           for (int q = 0; q < 4; ++q) { const int v0 = 32 * vb + 8 * q + 4 * hh; const f32x4 gn = *(const GAS f32x4*)(F.in[17] + v0);
;               v2u w; w.x = pk2(acc[4 * q] * rstd * gn.x * siluf_(bflo(ogc[q].x)), acc[4 * q + 1] * rstd * gn.y * siluf_(bfhi(ogc[q].x)));
;               w.y = pk2(acc[4 * q + 2] * rstd * gn.z * siluf_(bflo(ogc[q].y)), acc[4 * q + 3] * rstd * gn.w * siluf_(bfhi(ogc[q].y)));
;               *(v2u*)(MIX + (size_t)(tok0 + t) * DM + 512 + h * HD + v0) = w; } }
;         __syncthreads();
.LBB0_692:
	s_or_b64 exec, exec, s[24:25]
	s_waitcnt lgkmcnt(0)
	s_barrier
	v_add_u32_e32 v75, 0, v93
	v_lshlrev_b32_e32 v104, 16, v80
	ds_read_b128 v[100:103], v75 offset:52224
	s_lshl_b32 s10, s18, 4
	s_lshl_b32 s13, s18, 6
	v_mul_f32_e32 v75, 0xbfb8aa3b, v104
	v_and_b32_e32 v105, 0xffff0000, v80
	s_and_b32 s24, s10, 0xfffff800
	s_and_b32 s13, s13, 0x7c0
	v_exp_f32_e32 v75, v75
	v_lshlrev_b32_e32 v80, 16, v81
	v_and_b32_e32 v81, 0xffff0000, v81
	v_mul_f32_e32 v106, 0xbfb8aa3b, v105
	s_or_b32 s13, s24, s13
	v_mul_f32_e32 v107, 0xbfb8aa3b, v80
	v_mul_f32_e32 v108, 0xbfb8aa3b, v81
	v_exp_f32_e32 v110, v106
	v_add_u32_e32 v106, s13, v90
	v_exp_f32_e32 v111, v107
	v_exp_f32_e32 v112, v108
	v_ashrrev_i32_e32 v107, 31, v106
	s_waitcnt lgkmcnt(0)
	v_mov_b32_e32 v108, v101
	v_mov_b32_e32 v109, v102
	v_mov_b32_e32 v101, v103
	s_lshl_b32 s18, s18, 3
	v_lshlrev_b64 v[106:107], 11, v[106:107]
	v_add_f32_e32 v75, 1.0, v75
	v_pk_add_f32 v[100:101], v[108:109], v[100:101]
	s_and_b32 s10, s18, 0x300
	v_lshl_add_u64 v[102:103], s[50:51], 0, v[106:107]
	v_rcp_f32_e32 v106, v75
	v_add_f32_e32 v75, v100, v101
	v_lshl_add_u64 v[102:103], v[102:103], 0, s[10:11]
	v_fmamk_f32 v75, v75, 0x3c000000, v98
	v_add_f32_e32 v107, 1.0, v110
	v_add_f32_e32 v110, 1.0, v111
	v_add_f32_e32 v111, 1.0, v112
	v_lshl_add_u64 v[100:101], v[102:103], 0, v[54:55]
	v_rsq_f32_e32 v102, v75
	v_rcp_f32_e32 v107, v107
	v_rcp_f32_e32 v108, v110
	v_rcp_f32_e32 v109, v111
	v_pk_mul_f32 v[2:3], v[2:3], v[102:103] op_sel_hi:[1,0]
	v_pk_mul_f32 v[4:5], v[4:5], v[102:103] op_sel_hi:[1,0]
	v_pk_mul_f32 v[104:105], v[106:107], v[104:105]
	v_pk_mul_f32 v[80:81], v[108:109], v[80:81]
	v_add_co_u32_e32 v110, vcc, s19, v100
	s_mov_b32 s18, s16
	s_nop 0
	v_addc_co_u32_e32 v111, vcc, 0, v101, vcc
	v_lshl_add_u64 v[100:101], v[100:101], 0, s[14:15]
	s_andn2_b64 vcc, exec, s[20:21]
	v_pk_mul_f32 v[2:3], v[198:199], v[2:3]
	v_pk_mul_f32 v[4:5], v[200:201], v[4:5]
	v_pk_mul_f32 v[2:3], v[104:105], v[2:3]
	v_pk_mul_f32 v[4:5], v[80:81], v[4:5]
	v_cvt_pk_bf16_f32 v2, v2, v3
	v_cvt_pk_bf16_f32 v3, v4, v5
	global_store_dwordx2 v[110:111], v[2:3], off offset:1024
	v_lshlrev_b32_e32 v50, 16, v78
	v_and_b32_e32 v51, 0xffff0000, v78
	v_lshlrev_b32_e32 v52, 16, v79
	v_and_b32_e32 v53, 0xffff0000, v79
	v_mul_f32_e32 v75, 0xbfb8aa3b, v50
	v_mul_f32_e32 v78, 0xbfb8aa3b, v51
	v_mul_f32_e32 v79, 0xbfb8aa3b, v52
	v_mul_f32_e32 v80, 0xbfb8aa3b, v53
	v_exp_f32_e32 v75, v75
	v_exp_f32_e32 v78, v78
	v_exp_f32_e32 v79, v79
	v_exp_f32_e32 v80, v80
	v_add_f32_e32 v75, 1.0, v75
	v_add_f32_e32 v81, 1.0, v78
	v_add_f32_e32 v103, 1.0, v79
	v_add_f32_e32 v104, 1.0, v80
	v_rcp_f32_e32 v78, v75
	v_rcp_f32_e32 v79, v81
	v_rcp_f32_e32 v80, v103
	v_rcp_f32_e32 v81, v104
	v_pk_mul_f32 v[6:7], v[6:7], v[102:103] op_sel_hi:[1,0]
	v_pk_mul_f32 v[8:9], v[8:9], v[102:103] op_sel_hi:[1,0]
	v_pk_mul_f32 v[50:51], v[78:79], v[50:51]
	v_pk_mul_f32 v[52:53], v[80:81], v[52:53]
	v_pk_mul_f32 v[10:11], v[10:11], v[102:103] op_sel_hi:[1,0]
	v_pk_mul_f32 v[12:13], v[12:13], v[102:103] op_sel_hi:[1,0]
	v_pk_mul_f32 v[14:15], v[14:15], v[102:103] op_sel_hi:[1,0]
	v_pk_mul_f32 v[16:17], v[16:17], v[102:103] op_sel_hi:[1,0]
	v_cndmask_b32_e64 v75, 0, 1, s[22:23]
	v_xor_b32_e32 v99, v99, v75
	v_pk_mul_f32 v[2:3], v[202:203], v[6:7]
	v_pk_mul_f32 v[4:5], v[204:205], v[8:9]
	v_pk_mul_f32 v[2:3], v[50:51], v[2:3]
	v_pk_mul_f32 v[4:5], v[52:53], v[4:5]
	v_cvt_pk_bf16_f32 v2, v2, v3
	v_cvt_pk_bf16_f32 v3, v4, v5
	global_store_dwordx2 v[100:101], v[2:3], off offset:16
	v_lshlrev_b32_e32 v6, 16, v76
	v_and_b32_e32 v7, 0xffff0000, v76
	v_lshlrev_b32_e32 v8, 16, v77
	v_and_b32_e32 v9, 0xffff0000, v77
	v_mul_f32_e32 v50, 0xbfb8aa3b, v6
	v_mul_f32_e32 v51, 0xbfb8aa3b, v7
	v_mul_f32_e32 v52, 0xbfb8aa3b, v8
	v_mul_f32_e32 v53, 0xbfb8aa3b, v9
	v_exp_f32_e32 v50, v50
	v_exp_f32_e32 v51, v51
	v_exp_f32_e32 v52, v52
	v_exp_f32_e32 v53, v53
	v_add_f32_e32 v50, 1.0, v50
	v_add_f32_e32 v51, 1.0, v51
	v_add_f32_e32 v52, 1.0, v52
	v_add_f32_e32 v53, 1.0, v53
	v_rcp_f32_e32 v50, v50
	v_rcp_f32_e32 v51, v51
	v_rcp_f32_e32 v52, v52
	v_rcp_f32_e32 v53, v53
	v_pk_mul_f32 v[6:7], v[50:51], v[6:7]
	v_pk_mul_f32 v[8:9], v[52:53], v[8:9]
	v_pk_mul_f32 v[2:3], v[10:11], v[206:207]
	v_pk_mul_f32 v[4:5], v[12:13], v[208:209]
	v_pk_mul_f32 v[2:3], v[6:7], v[2:3]
	v_pk_mul_f32 v[4:5], v[8:9], v[4:5]
	v_cvt_pk_bf16_f32 v2, v2, v3
	v_cvt_pk_bf16_f32 v3, v4, v5
	global_store_dwordx2 v[100:101], v[2:3], off offset:32
	v_lshlrev_b32_e32 v10, 16, v70
	v_and_b32_e32 v11, 0xffff0000, v70
	v_lshlrev_b32_e32 v12, 16, v71
	v_and_b32_e32 v13, 0xffff0000, v71
	v_mul_f32_e32 v214, 0xbfb8aa3b, v10
	v_mul_f32_e32 v215, 0xbfb8aa3b, v11
	v_mul_f32_e32 v216, 0xbfb8aa3b, v12
	v_mul_f32_e32 v217, 0xbfb8aa3b, v13
	v_exp_f32_e32 v214, v214
	v_exp_f32_e32 v215, v215
	v_exp_f32_e32 v216, v216
	v_exp_f32_e32 v217, v217
	v_add_f32_e32 v214, 1.0, v214
	v_add_f32_e32 v215, 1.0, v215
	v_add_f32_e32 v216, 1.0, v216
	v_add_f32_e32 v217, 1.0, v217
	v_rcp_f32_e32 v214, v214
	v_rcp_f32_e32 v215, v215
	v_rcp_f32_e32 v216, v216
	v_rcp_f32_e32 v217, v217
	v_pk_mul_f32 v[10:11], v[214:215], v[10:11]
	v_pk_mul_f32 v[12:13], v[216:217], v[12:13]
	v_pk_mul_f32 v[2:3], v[14:15], v[210:211]
	v_pk_mul_f32 v[4:5], v[16:17], v[212:213]
	v_pk_mul_f32 v[2:3], v[10:11], v[2:3]
	v_pk_mul_f32 v[4:5], v[12:13], v[4:5]
	v_cvt_pk_bf16_f32 v2, v2, v3
	v_cvt_pk_bf16_f32 v3, v4, v5
	global_store_dwordx2 v[100:101], v[2:3], off offset:48
	s_and_saveexec_b64 s[28:29], s[92:93]
	s_cbranch_execz my_hgq_c
	s_cbranch_vccz my_hgq_n
	s_waitcnt vmcnt(16)
	s_branch my_hgq_w
; #define LAS __attribute__((address_space(3)))
; __device__ __forceinline__ void hgC_loop(Frame& F, unsigned* ctr) {
;     ...
;     for (;;) {
;         const int bh = item >> 5, chunk = item & 31, b = bh >> 2, h = bh & 3, tok0 = b * PB_T + chunk * 64;
; #pragma unroll
;         for (int i = 0; i < 4; ++i) { const int p = tid + 512 * i; *(LAS v4u*)(SC + (p >> 4) * HG_LDQ + (p & 15) * 8) = sc[i]; }
; #pragma unroll
;         for (int i = 0; i < 2; ++i) { const int p = tid + 512 * i; *(LAS v4u*)(Qh + (p >> 4) * HG_LDQ + (p & 15) * 8) = qh[i]; }
;         f32x16 acc;
;         acc[0] = bflo(oi[0].x); acc[1] = bfhi(oi[0].x); acc[2] = bflo(oi[0].y); acc[3] = bfhi(oi[0].y); acc[4] = bflo(oi[0].z); acc[5] = bfhi(oi[0].z); acc[6] = bflo(oi[0].w); acc[7] = bfhi(oi[0].w);
;         acc[8] = bflo(oi[1].x); acc[9] = bfhi(oi[1].x); acc[10] = bflo(oi[1].y); acc[11] = bfhi(oi[1].y); acc[12] = bflo(oi[1].z); acc[13] = bfhi(oi[1].z); acc[14] = bflo(oi[1].w); acc[15] = bfhi(oi[1].w);
;         v2u ogc[4];
; #pragma unroll
;         for (int q = 0; q < 4; ++q) ogc[q] = og[q];
;         if (tid == 0) slot[par] = (int)__hip_atomic_fetch_add(ctr, 1u, __ATOMIC_RELAXED, __HIP_MEMORY_SCOPE_AGENT);
;         if (nxt < 1024) HGC_FETCH(nxt);
;         __syncthreads();
;         const int nn = slot[par];
;     ...
;         if (nxt >= 1024) break;
;         item = nxt; nxt = nn; par ^= 1;
my_hgq_n:
	s_waitcnt vmcnt(4)
my_hgq_w:
	ds_write_b32 v55, v236 offset:53256
my_hgq_c:
	s_or_b64 exec, exec, s[28:29]
	s_waitcnt lgkmcnt(0)
	s_barrier
	ds_read_b32 v237, v55 offset:53256
	s_waitcnt lgkmcnt(0)
	v_readfirstlane_b32 s17, v237
	s_nop 3
	s_cbranch_vccz .LBB0_701
.LBB0_693:
	s_mov_b32 s16, s17
	s_waitcnt vmcnt(15)
	ds_write_b128 v94, v[18:21]
	s_waitcnt vmcnt(14)
	ds_write_b128 v95, v[22:25]
	s_waitcnt vmcnt(13)
	ds_write_b128 v94, v[26:29] offset:17408
	s_waitcnt vmcnt(12)
	ds_write_b128 v96, v[30:33]
	s_waitcnt vmcnt(11)
	ds_write_b128 v94, v[34:37] offset:34816
	s_waitcnt vmcnt(10)
	ds_write_b128 v95, v[38:41] offset:34816
	s_cmpk_lt_i32 s16, 0x400
	s_cselect_b64 s[22:23], -1, 0
	s_cmpk_gt_i32 s16, 0x3ff
	s_cselect_b64 s[20:21], -1, 0
	s_waitcnt vmcnt(8)
	v_mov_b64_e32 v[50:51], v[42:43]
	v_mov_b64_e32 v[52:53], v[44:45]
	v_mov_b64_e32 v[6:7], v[46:47]
	v_mov_b64_e32 v[8:9], v[48:49]
	s_and_b64 vcc, exec, s[20:21]
	s_waitcnt vmcnt(4)
	v_mov_b64_e32 v[80:81], v[82:83]
	v_mov_b64_e32 v[78:79], v[84:85]
	v_mov_b64_e32 v[76:77], v[86:87]
	v_mov_b64_e32 v[70:71], v[88:89]
	s_and_saveexec_b64 s[28:29], s[92:93]
	s_cbranch_execz my_hgq_a
	v_mov_b32_e32 v237, 1
	global_atomic_add v236, v55, v237, s[4:5] sc0
my_hgq_a:
	s_or_b64 exec, exec, s[28:29]
	s_cbranch_vccnz .LBB0_699
	s_ashr_i32 s17, s16, 31
	s_lshl_b64 s[24:25], s[16:17], 15
	v_lshl_add_u64 v[2:3], v[64:65], 0, s[24:25]
	v_lshl_add_u64 v[4:5], v[2:3], 0, v[56:57]
	s_lshl_b64 s[26:27], s[16:17], 14
	v_lshl_add_u64 v[10:11], v[2:3], 0, v[58:59]
	global_load_dwordx4 v[18:21], v[4:5], off
	global_load_dwordx4 v[22:25], v[10:11], off
	v_lshl_add_u64 v[4:5], v[2:3], 0, v[60:61]
	v_lshl_add_u64 v[2:3], v[2:3], 0, v[62:63]
	s_lshl_b32 s10, s16, 4
	s_lshl_b32 s13, s16, 6
	global_load_dwordx4 v[26:29], v[4:5], off
	global_load_dwordx4 v[30:33], v[2:3], off
	v_lshl_add_u64 v[2:3], v[66:67], 0, s[26:27]
	s_and_b32 s10, s10, 0xfffff800
	v_lshl_add_u64 v[4:5], v[2:3], 0, v[56:57]
	v_lshl_add_u64 v[2:3], v[2:3], 0, v[58:59]
	s_and_b32 s13, s13, 0x7c0
	global_load_dwordx4 v[34:37], v[4:5], off
	global_load_dwordx4 v[38:41], v[2:3], off
	v_lshl_add_u64 v[2:3], v[68:69], 0, s[26:27]
	s_or_b32 s10, s10, s13
	global_load_dwordx4 v[42:45], v[2:3], off offset:16
	global_load_dwordx4 v[46:49], v[2:3], off
	v_add_u32_e32 v2, s10, v90
	v_ashrrev_i32_e32 v3, 31, v2
	v_lshlrev_b64 v[2:3], 12, v[2:3]
	s_lshl_b32 s10, s16, 3
	v_lshl_add_u64 v[2:3], s[56:57], 0, v[2:3]
	s_and_b32 s10, s10, 0x300
	v_lshl_add_u64 v[2:3], v[2:3], 0, s[10:11]
	s_mov_b32 s13, s11
	v_lshl_add_u64 v[2:3], v[2:3], 0, s[12:13]
	v_mov_b32_e32 v75, v55
	v_lshl_add_u64 v[2:3], v[2:3], 0, v[74:75]
	global_load_dwordx2 v[82:83], v[2:3], off offset:3072
	global_load_dwordx2 v[84:85], v[2:3], off offset:3088
	global_load_dwordx2 v[86:87], v[2:3], off offset:3104
	global_load_dwordx2 v[88:89], v[2:3], off offset:3120
